# queue loop top: wait only for the ticket atomic (vmcnt(8)/vmcnt(4)) instead of draining the item's final stores
# speedup vs baseline: 1.0027x; 1.0027x over previous
; #define ATT_LDS_BAR() asm volatile("s_waitcnt lgkmcnt(0)\n\ts_barrier" ::: "memory")
; __global__ void __launch_bounds__(NWAVES * 64, 2) fwd(Args args) {
;     ...
;         for (;;) {
;             if (tid == 0) MISC[16] = nx;
;             ATT_LDS_BAR();
;             const int idx = __builtin_amdgcn_readfirstlane((int)MISC[16]);
;     ...
;                 conv_unit(idx - n_att - w_p2, Ub, ws + WS_CW16, args.in[12], args.in[13], args.in[14], MIX, lds, tid, wave, lane, conv_w_staged, nx, ctl + CW_QUEUE);
.LBB0_395:
	s_waitcnt vmcnt(4)
	v_mov_b32_e32 v188, v26
	s_mov_b64 s[26:27], s[2:3]
	s_branch .Lq_top_nowait

; __global__ void __launch_bounds__(NWAVES * 64, 2) fwd(Args args) {
;     ...
;             if (tid == 0) MISC[16] = nx;
.Lq_top_nowait:
	v_mov_b32_e32 v219, v188

; #define ATT_LDS_BAR() asm volatile("s_waitcnt lgkmcnt(0)\n\ts_barrier" ::: "memory")
; __global__ void __launch_bounds__(NWAVES * 64, 2) fwd(Args args) {
;     ...
;         for (;;) {
;             if (tid == 0) MISC[16] = nx;
;             ATT_LDS_BAR();
;             const int idx = __builtin_amdgcn_readfirstlane((int)MISC[16]);
;             ATT_LDS_BAR();
;             if (idx >= n_att + w_p2 + N_CONV_UNITS) break;
;             if (idx < n_att) {
;                 att::attn_unit(idx, Bn, Cn, lam, pre, sidx, Qb, Kimg, Vimg, MIX, args.in[10], (char*)lds_raw, (float*)(ws + WS_SLAB), slabs_cnt, MISC + 17, nx, ctl + CW_QUEUE);
.LBB0_461:
	s_waitcnt vmcnt(8)
	v_mov_b32_e32 v188, v219
	s_movk_i32 s18, 0x4000
	s_xor_b64 s[4:5], s[26:27], -1
	s_andn2_b64 vcc, exec, s[2:3]
	s_cbranch_vccnz .Lq_top_nowait
